# v2 stack + XCD-local grid barriers where the next phase only touches class-local bytes (full barriers kept before the ACT-layout switches)
# speedup vs baseline: 1.0379x; 1.0253x over previous
_Z14fwd_megakernel4Args:
	s_load_dwordx4 s[4:7], s[0:1], 0xa0
	s_load_dwordx2 s[52:53], s[0:1], 0xb8
	s_load_dword s3, s[0:1], 0xc0
	v_and_b32_e32 v240, 0x3ff, v0
	s_add_u32 s34, s0, 0xb8
	v_mov_b32_e32 v1, v240
	s_waitcnt lgkmcnt(0)
	v_writelane_b32 v254, s4, 0
	s_mov_b32 s74, s2
	s_addc_u32 s35, s1, 0
	v_writelane_b32 v254, s5, 1
	v_writelane_b32 v254, s6, 2
	v_writelane_b32 v254, s7, 3
	s_nop 0
	v_readfirstlane_b32 s58, v1
	v_cmp_eq_u32_e32 vcc, 0, v1
	s_and_saveexec_b64 s[20:21], vcc
	s_cbranch_execz .LBB0_2
	s_load_dwordx16 s[4:19], s[0:1], 0x0
	s_add_i32 s2, 0, 0x20200
	v_mov_b32_e32 v2, 0
	v_mov_b32_e32 v3, s2
	s_add_i32 s2, 0, 0x20204
	ds_write_b32 v3, v2
	v_mov_b32_e32 v3, s2
	s_add_i32 s2, 0, 0x20400
	s_load_dwordx16 s[36:51], s[0:1], 0x40
	ds_write_b32 v3, v2
	v_mov_b32_e32 v3, 0x20208
	ds_write_b32 v3, v2
	s_waitcnt lgkmcnt(0)
	v_mov_b32_e32 v2, s4
	v_mov_b32_e32 v3, s5
	v_mov_b32_e32 v4, s6
	v_mov_b32_e32 v5, s7
	v_mov_b32_e32 v6, s2
	s_add_i32 s2, 0, 0x20410
	ds_write_b128 v6, v[2:5]
	v_mov_b32_e32 v2, s8
	v_mov_b32_e32 v3, s9
	v_mov_b32_e32 v4, s10
	v_mov_b32_e32 v5, s11
	v_mov_b32_e32 v6, s2
	s_add_i32 s2, 0, 0x20420
	ds_write_b128 v6, v[2:5]
	v_mov_b32_e32 v2, s12
	v_mov_b32_e32 v3, s13
	v_mov_b32_e32 v4, s14
	v_mov_b32_e32 v5, s15
	v_mov_b32_e32 v6, s2
	s_add_i32 s2, 0, 0x20430
	ds_write_b128 v6, v[2:5]
	v_mov_b32_e32 v2, s16
	v_mov_b32_e32 v3, s17
	v_mov_b32_e32 v4, s18
	v_mov_b32_e32 v5, s19
	v_mov_b32_e32 v6, s2
	s_add_i32 s2, 0, 0x20440
	s_load_dwordx8 s[4:11], s[0:1], 0x80
	ds_write_b128 v6, v[2:5]
	v_mov_b32_e32 v2, s36
	v_mov_b32_e32 v3, s37
	v_mov_b32_e32 v4, s38
	v_mov_b32_e32 v5, s39
	v_mov_b32_e32 v6, s2
	s_add_i32 s2, 0, 0x20450
	ds_write_b128 v6, v[2:5]
	v_mov_b32_e32 v2, s40
	v_mov_b32_e32 v3, s41
	v_mov_b32_e32 v4, s42
	v_mov_b32_e32 v5, s43
	v_mov_b32_e32 v6, s2
	s_add_i32 s2, 0, 0x20460
	ds_write_b128 v6, v[2:5]
	v_mov_b32_e32 v2, s44
	v_mov_b32_e32 v3, s45
	v_mov_b32_e32 v4, s46
	v_mov_b32_e32 v5, s47
	v_mov_b32_e32 v6, s2
	s_add_i32 s2, 0, 0x20470
	ds_write_b128 v6, v[2:5]
	v_mov_b32_e32 v2, s48
	v_mov_b32_e32 v3, s49
	v_mov_b32_e32 v4, s50
	v_mov_b32_e32 v5, s51
	v_mov_b32_e32 v6, s2
	s_add_i32 s2, 0, 0x20480
	ds_write_b128 v6, v[2:5]
	s_waitcnt lgkmcnt(0)
	v_mov_b32_e32 v2, s4
	v_mov_b32_e32 v3, s5
	v_mov_b32_e32 v4, s6
	v_mov_b32_e32 v5, s7
	v_mov_b32_e32 v6, s2
	s_add_i32 s2, 0, 0x20490
	ds_write_b128 v6, v[2:5]
	v_mov_b32_e32 v2, s8
	v_mov_b32_e32 v3, s9
	v_mov_b32_e32 v4, s10
	v_mov_b32_e32 v5, s11
	v_mov_b32_e32 v6, s2
	ds_write_b128 v6, v[2:5]
.LBB0_2:
	s_or_b64 exec, exec, s[20:21]
	s_load_dwordx4 s[4:7], s[0:1], 0xa0
	s_waitcnt lgkmcnt(0)
	s_barrier
	s_getreg_b32 s2, hwreg(HW_REG_XCC_ID, 0, 4)
	s_add_u32 s10, s6, 0x10000
	s_addc_u32 s11, s7, 0
	s_and_b32 s33, s2, 15
	v_cmp_ne_u32_e64 s[4:5], 0, v240
	v_mov_b64_e32 v[6:7], s[6:7]
	v_cmp_eq_u32_e64 s[8:9], 0, v240
	s_mov_b64 s[6:7], exec
	s_nop 0
	v_writelane_b32 v254, s8, 4
	s_nop 1
	v_writelane_b32 v254, s9, 5
	s_and_b64 s[8:9], s[6:7], s[8:9]
	s_mov_b64 exec, s[8:9]
	s_cbranch_execz .LBB0_6
	s_load_dwordx4 s[16:19], s[0:1], 0xa0
	s_mov_b64 s[12:13], exec
	v_mbcnt_lo_u32_b32 v2, s12, 0
	v_mbcnt_hi_u32_b32 v2, s13, v2
	v_cmp_eq_u32_e32 vcc, 0, v2
	s_waitcnt lgkmcnt(0)
	v_mov_b64_e32 v[6:7], s[18:19]
	s_and_saveexec_b64 s[8:9], vcc
	s_cbranch_execz .LBB0_5
	s_lshl_b32 s2, s33, 8
	s_bcnt1_i32_b64 s12, s[12:13]
	v_mov_b32_e32 v2, s2
	v_mov_b32_e32 v3, s12
	global_atomic_add v2, v3, s[10:11] offset:1024
	s_and_b32 s2, s74, 7
	s_lshl_b32 s2, s2, 2
	s_lshl_b32 s12, 1, s33
	v_mov_b32_e32 v2, s2
	v_mov_b32_e32 v3, s12
	global_atomic_or v2, v3, s[10:11]
	s_load_dwordx2 s[12:13], s[0:1], 0xa8
	s_waitcnt lgkmcnt(0)
	v_mov_b64_e32 v[6:7], s[12:13]

.LBB0_488:
	v_mov_b32_e32 v5, 0x20208
	ds_read_b32 v4, v5
	s_waitcnt lgkmcnt(0)
	v_readfirstlane_b32 s2, v4
	s_cmp_lg_u32 s2, 0
	s_cbranch_scc1 .Lxb0_known
	v_readlane_b32 s6, v254, 7
	s_mov_b32 s2, 1
	s_nop 2
	s_cmp_lg_u32 s6, 0x100
	s_cbranch_scc1 .Lxb0_store
	v_readlane_b32 s6, v254, 14
	v_readlane_b32 s7, v254, 15
	v_mov_b32_e32 v5, 0
	v_mov_b32_e32 v6, 0
	s_nop 4
	global_load_dword v4, v6, s[6:7] offset:-512 sc1
	s_waitcnt vmcnt(0)
	v_bcnt_u32_b32 v4, v4, 0
	v_xor_b32_e32 v4, 1, v4
	v_or_b32_e32 v5, v5, v4
	global_load_dword v4, v6, s[6:7] offset:-508 sc1
	s_waitcnt vmcnt(0)
	v_bcnt_u32_b32 v4, v4, 0
	v_xor_b32_e32 v4, 1, v4
	v_or_b32_e32 v5, v5, v4
	global_load_dword v4, v6, s[6:7] offset:-504 sc1
	s_waitcnt vmcnt(0)
	v_bcnt_u32_b32 v4, v4, 0
	v_xor_b32_e32 v4, 1, v4
	v_or_b32_e32 v5, v5, v4
	global_load_dword v4, v6, s[6:7] offset:-500 sc1
	s_waitcnt vmcnt(0)
	v_bcnt_u32_b32 v4, v4, 0
	v_xor_b32_e32 v4, 1, v4
	v_or_b32_e32 v5, v5, v4
	global_load_dword v4, v6, s[6:7] offset:-496 sc1
	s_waitcnt vmcnt(0)
	v_bcnt_u32_b32 v4, v4, 0
	v_xor_b32_e32 v4, 1, v4
	v_or_b32_e32 v5, v5, v4
	global_load_dword v4, v6, s[6:7] offset:-492 sc1
	s_waitcnt vmcnt(0)
	v_bcnt_u32_b32 v4, v4, 0
	v_xor_b32_e32 v4, 1, v4
	v_or_b32_e32 v5, v5, v4
	global_load_dword v4, v6, s[6:7] offset:-488 sc1
	s_waitcnt vmcnt(0)
	v_bcnt_u32_b32 v4, v4, 0
	v_xor_b32_e32 v4, 1, v4
	v_or_b32_e32 v5, v5, v4
	global_load_dword v4, v6, s[6:7] offset:-484 sc1
	s_waitcnt vmcnt(0)
	v_bcnt_u32_b32 v4, v4, 0
	v_xor_b32_e32 v4, 1, v4
	v_or_b32_e32 v5, v5, v4
	s_nop 1
	v_readfirstlane_b32 s6, v5
	s_cmp_eq_u32 s6, 0
	s_cselect_b32 s2, 2, 1
.Lxb0_store:
	v_mov_b32_e32 v5, 0x20208
	v_mov_b32_e32 v4, s2
	ds_write_b32 v5, v4

.LBB0_502:
	s_andn2_saveexec_b64 s[2:3], s[4:5]
	s_cbranch_execz .LBB0_520
	s_mov_b64 s[4:5], exec
	v_mov_b32_e32 v0, 0x20208
	ds_read_b32 v3, v0
	s_waitcnt lgkmcnt(0)
	v_readfirstlane_b32 s2, v3
	s_cmp_lg_u32 s2, 0
	s_cbranch_scc1 .Lxb1_known
	v_readlane_b32 s6, v254, 7
	s_mov_b32 s2, 1
	s_nop 2
	s_cmp_lg_u32 s6, 0x100
	s_cbranch_scc1 .Lxb1_store
	v_readlane_b32 s6, v254, 14
	v_readlane_b32 s7, v254, 15
	v_mov_b32_e32 v3, 0
	s_nop 4
	v_mov_b32_e32 v0, 0
	global_load_dwordx2 v[4:5], v0, s[6:7] offset:-512 sc1
	s_waitcnt vmcnt(0)
	v_bcnt_u32_b32 v0, v4, 0
	v_bcnt_u32_b32 v6, v5, 0
	v_xor_b32_e32 v0, 1, v0
	v_xor_b32_e32 v6, 1, v6
	v_or3_b32 v3, v3, v0, v6
	v_mov_b32_e32 v0, 0
	global_load_dwordx2 v[4:5], v0, s[6:7] offset:-504 sc1
	s_waitcnt vmcnt(0)
	v_bcnt_u32_b32 v0, v4, 0
	v_bcnt_u32_b32 v6, v5, 0
	v_xor_b32_e32 v0, 1, v0
	v_xor_b32_e32 v6, 1, v6
	v_or3_b32 v3, v3, v0, v6
	v_mov_b32_e32 v0, 0
	global_load_dwordx2 v[4:5], v0, s[6:7] offset:-496 sc1
	s_waitcnt vmcnt(0)
	v_bcnt_u32_b32 v0, v4, 0
	v_bcnt_u32_b32 v6, v5, 0
	v_xor_b32_e32 v0, 1, v0
	v_xor_b32_e32 v6, 1, v6
	v_or3_b32 v3, v3, v0, v6
	v_mov_b32_e32 v0, 0
	global_load_dwordx2 v[4:5], v0, s[6:7] offset:-488 sc1
	s_waitcnt vmcnt(0)
	v_bcnt_u32_b32 v0, v4, 0
	v_bcnt_u32_b32 v6, v5, 0
	v_xor_b32_e32 v0, 1, v0
	v_xor_b32_e32 v6, 1, v6
	v_or3_b32 v3, v3, v0, v6
	s_nop 1
	v_readfirstlane_b32 s6, v3
	s_cmp_eq_u32 s6, 0
	s_cselect_b32 s2, 2, 1
.Lxb1_store:
	v_mov_b32_e32 v0, 0x20208
	v_mov_b32_e32 v3, s2
	ds_write_b32 v0, v3
.Lxb1_known:
	s_cmp_eq_u32 s2, 2
	s_cbranch_scc0 .Lxb1_slow
	s_cmp_eq_u32 s71, 3
	s_cbranch_scc1 .Lxb1_slow
	s_cmp_eq_u32 s71, 6
	s_cbranch_scc1 .Lxb1_slow
	s_cmp_eq_u32 s71, 10
	s_cbranch_scc1 .Lxb1_slow
	s_cmp_eq_u32 s71, 13
	s_cbranch_scc0 .Lxb1_fast
.Lxb1_slow:
	buffer_wbl2 sc1
	s_waitcnt lgkmcnt(0)
	s_waitcnt vmcnt(0)
	v_mbcnt_lo_u32_b32 v0, s4, 0
	v_mbcnt_hi_u32_b32 v0, s5, v0
	v_cmp_eq_u32_e32 vcc, 0, v0
	s_and_saveexec_b64 s[6:7], vcc
	s_cbranch_execz .LBB0_505
	s_bcnt1_i32_b64 s2, s[4:5]
	v_mov_b32_e32 v3, s2
	v_readlane_b32 s2, v254, 16
	v_readlane_b32 s3, v254, 17
	s_nop 4
	global_atomic_add v3, v1, v3, s[2:3] sc0

.Lxb1_fast:
	s_waitcnt vmcnt(0)
	buffer_inv sc1
	global_atomic_add v[176:177], v244, off
	s_waitcnt vmcnt(0)

.LBB0_932:
	s_andn2_saveexec_b64 s[2:3], s[2:3]
	s_cbranch_execz .LBB0_950
	s_mov_b64 s[2:3], exec
	v_mov_b32_e32 v2, 0x20208
	ds_read_b32 v3, v2
	s_waitcnt lgkmcnt(0)
	v_readfirstlane_b32 s4, v3
	s_cmp_eq_u32 s4, 2
	s_cbranch_scc1 .Lxb2_fast
	buffer_wbl2 sc1
	s_waitcnt lgkmcnt(0)
	s_waitcnt vmcnt(0)
	v_mbcnt_lo_u32_b32 v1, s2, 0
	v_mbcnt_hi_u32_b32 v1, s3, v1
	v_cmp_eq_u32_e32 vcc, 0, v1
	s_and_saveexec_b64 s[4:5], vcc
	s_cbranch_execz .LBB0_935
	s_bcnt1_i32_b64 s2, s[2:3]
	v_mov_b32_e32 v3, s2
	v_readlane_b32 s2, v254, 16
	v_mov_b32_e32 v2, 0
	v_readlane_b32 s3, v254, 17
	s_nop 4
	global_atomic_add v2, v2, v3, s[2:3] sc0

.Lxb2_fast:
	v_mov_b32_e32 v0, 1
	s_waitcnt vmcnt(0)
	buffer_inv sc1
	global_atomic_add v[176:177], v0, off
	s_waitcnt vmcnt(0)
